# WD: layer-1 in-proj weight conversion moved out of the prologue into the slack of layer 0's in-proj phase (the 64 workgroups with one tile pair less); prologue converts layer 0 only with the hand-writ
# speedup vs baseline: 1.0135x; 1.0093x over previous
.LBB0_24:
	s_or_b64 exec, exec, s[0:1]
	v_readlane_b32 s12, v234, 4
	v_readlane_b32 s13, v234, 5
	s_nop 3
	s_add_u32 s14, s12, 0x3c70
	s_addc_u32 s15, s13, 0
	s_add_u32 s16, s14, 0x3c70
	s_addc_u32 s17, s15, 0
	s_add_u32 s18, s16, 0x3c70
	s_addc_u32 s19, s17, 0
	s_add_u32 s20, s18, 0x3c70
	s_addc_u32 s21, s19, 0
	s_add_u32 s22, s20, 0x3c70
	s_addc_u32 s23, s21, 0
	s_add_u32 s24, s22, 0x3c70
	s_addc_u32 s25, s23, 0
	s_add_u32 s26, s24, 0x3c70
	s_addc_u32 s27, s25, 0
	s_add_u32 s28, s80, 0x400000
	s_addc_u32 s29, s81, 0
	v_mov_b32_e32 v101, 0x8421100
	v_mov_b32_e32 v102, 0x300
	v_cmp_gt_u32_e32 vcc, 0x1f000, v4
	s_nop 1
	v_cndmask_b32_e64 v0, 0, v4, vcc
	v_lshrrev_b32_e32 v1, 6, v0
	v_lshrrev_b32_e32 v2, 2, v1
	v_mul_hi_u32 v12, v2, v101
	v_mul_u32_u24_e32 v3, 31, v12
	v_sub_u32_e32 v3, v2, v3
	v_and_b32_e32 v8, 3, v1
	v_lshl_or_b32 v3, v3, 2, v8
	v_bfe_u32 v8, v0, 3, 3
	v_lshl_or_b32 v3, v3, 3, v8
	v_and_b32_e32 v8, 7, v0
	v_lshl_or_b32 v2, v12, 3, v8
	v_lshlrev_b32_e32 v8, 2, v3
	v_lshrrev_b32_e32 v9, 4, v3
	v_and_b32_e32 v10, 60, v8
	v_cmp_lt_u32_e32 vcc, 11, v9
	s_nop 1
	v_cndmask_b32_e64 v1, 0, 4, vcc
	v_cmp_lt_u32_e32 vcc, 35, v9
	s_nop 1
	v_cndmask_b32_e64 v1, v1, 28, vcc
	v_bfe_u32 v12, v10, 4, 1
	v_lshrrev_b32_e32 v3, 5, v10
	v_sub_u32_e32 v12, v12, v3
	v_lshlrev_b32_e32 v12, 4, v12
	v_add_u32_e32 v3, 0xffffffd4, v9
	v_cmp_gt_u32_e32 vcc, 8, v3
	s_nop 1
	v_cndmask_b32_e64 v12, 0, v12, vcc
	v_add3_u32 v1, v8, v1, v12
	v_add_u32_e32 v3, 0x900, v10
	v_cmp_eq_u32_e32 vcc, 0, v10
	s_nop 1
	v_cndmask_b32_e32 v3, v3, v102, vcc
	v_cmp_eq_u32_e32 vcc, 60, v9
	s_nop 1
	v_cndmask_b32_e32 v1, v1, v3, vcc
	v_lshl_or_b32 v3, v9, 6, v10
	v_cmp_gt_u32_e32 vcc, 0xf1c, v3
	s_nop 1
	v_cndmask_b32_e64 v100, 0, 1, vcc
	s_nop 1
	v_cndmask_b32_e64 v1, 0, v1, vcc
	v_mul_u32_u24_e32 v14, 0x1e380, v2
	v_lshl_add_u32 v14, v1, 2, v14
	v_lshrrev_b32_e32 v12, 7, v2
	v_mul_u32_u24_e32 v15, 0x7c0000, v12
	v_lshl_add_u32 v15, v8, 11, v15
	v_and_b32_e32 v12, 0x7f, v2
	v_lshl_add_u32 v15, v12, 4, v15
	v_add_u32_e32 v16, 0x1000, v15
	global_load_dwordx4 v[20:23], v14, s[12:13]
	global_load_dwordx4 v[24:27], v14, s[14:15]
	global_load_dwordx4 v[28:31], v14, s[16:17]
	global_load_dwordx4 v[32:35], v14, s[18:19]
	global_load_dwordx4 v[36:39], v14, s[20:21]
	global_load_dwordx4 v[40:43], v14, s[22:23]
	global_load_dwordx4 v[44:47], v14, s[24:25]
	global_load_dwordx4 v[48:51], v14, s[26:27]
	s_waitcnt vmcnt(0)
	v_cvt_pk_bf16_f32 v84, v20, v24
	v_cvt_pk_bf16_f32 v85, v28, v32
	v_cvt_pk_bf16_f32 v86, v36, v40
	v_cvt_pk_bf16_f32 v87, v44, v48
	v_cvt_pk_bf16_f32 v88, v21, v25
	v_cvt_pk_bf16_f32 v89, v29, v33
	v_cvt_pk_bf16_f32 v90, v37, v41
	v_cvt_pk_bf16_f32 v91, v45, v49
	v_cvt_pk_bf16_f32 v92, v22, v26
	v_cvt_pk_bf16_f32 v93, v30, v34
	v_cvt_pk_bf16_f32 v94, v38, v42
	v_cvt_pk_bf16_f32 v95, v46, v50
	v_cvt_pk_bf16_f32 v96, v23, v27
	v_cvt_pk_bf16_f32 v97, v31, v35
	v_cvt_pk_bf16_f32 v98, v39, v43
	v_cvt_pk_bf16_f32 v99, v47, v51
	v_cmp_ne_u32_e32 vcc, 0, v100
	s_nop 1
	v_cndmask_b32_e64 v84, 0, v84, vcc
	v_cndmask_b32_e64 v85, 0, v85, vcc
	v_cndmask_b32_e64 v86, 0, v86, vcc
	v_cndmask_b32_e64 v87, 0, v87, vcc
	v_cndmask_b32_e64 v88, 0, v88, vcc
	v_cndmask_b32_e64 v89, 0, v89, vcc
	v_cndmask_b32_e64 v90, 0, v90, vcc
	v_cndmask_b32_e64 v91, 0, v91, vcc
	v_cndmask_b32_e64 v92, 0, v92, vcc
	v_cndmask_b32_e64 v93, 0, v93, vcc
	v_cndmask_b32_e64 v94, 0, v94, vcc
	v_cndmask_b32_e64 v95, 0, v95, vcc
	v_cndmask_b32_e64 v96, 0, v96, vcc
	v_cndmask_b32_e64 v97, 0, v97, vcc
	v_cndmask_b32_e64 v98, 0, v98, vcc
	v_cndmask_b32_e64 v99, 0, v99, vcc
	v_cmp_gt_u32_e32 vcc, 0x1f000, v4
	s_and_saveexec_b64 s[6:7], vcc
	global_store_dwordx4 v15, v[84:87], s[28:29]
	global_store_dwordx4 v15, v[88:91], s[28:29] offset:2048
	global_store_dwordx4 v16, v[92:95], s[28:29]
	global_store_dwordx4 v16, v[96:99], s[28:29] offset:2048
	s_or_b64 exec, exec, s[6:7]
	s_mov_b32 s61, 0
	s_mov_b64 s[0:1], 0
	s_lshl_b64 s[12:13], s[60:61], 8
	v_cmp_gt_i64_e32 vcc, s[0:1], v[4:5]
	s_and_saveexec_b64 s[14:15], vcc
	v_writelane_b32 v234, s74, 36
	s_nop 1
	v_writelane_b32 v234, s75, 37
	v_writelane_b32 v234, s60, 38
	s_nop 1
	v_writelane_b32 v234, s61, 39
	s_cbranch_execz .LBB0_97
	v_readlane_b32 s52, v234, 2
	v_readlane_b32 s60, v234, 10
	v_readlane_b32 s61, v234, 11
	s_add_u32 s16, s80, 0x400000
	v_readlane_b32 s53, v234, 3
	v_readlane_b32 s54, v234, 4
	v_readlane_b32 s55, v234, 5
	v_readlane_b32 s56, v234, 6
	v_readlane_b32 s60, v234, 38
	v_readlane_b32 s74, v234, 36
	s_addc_u32 s17, s81, 0
	s_mov_b64 s[18:19], 0
	s_mov_b32 s44, 0x84210842
	s_mov_b32 s45, 0x10842109
	v_mov_b32_e32 v9, 0
	s_movk_i32 s46, 0xf80
	s_movk_i32 s47, 0xffc0
	s_mov_b32 s48, 0xf1c000
	v_readlane_b32 s61, v234, 39
	v_readlane_b32 s75, v234, 37
	v_mov_b64_e32 v[10:11], s[54:55]
	s_movk_i32 s49, 0x3c70
	s_movk_i32 s50, 0x3000
	s_movk_i32 s51, 0x7000
	s_mov_b32 s52, 0xb000
	s_mov_b32 s53, 0xf000
	s_mov_b32 s54, 0x12000
	s_mov_b32 s55, 0x16000
	s_mov_b32 s56, 0x1a000
	s_mov_b64 s[20:21], 0xf7fff
	v_mov_b64_e32 v[0:1], v[4:5]
	v_readlane_b32 s57, v234, 7
	v_readlane_b32 s58, v234, 8
	v_readlane_b32 s59, v234, 9
	v_readlane_b32 s62, v234, 12
	v_readlane_b32 s63, v234, 13
	v_readlane_b32 s64, v234, 14
	v_readlane_b32 s65, v234, 15
	v_readlane_b32 s66, v234, 16
	v_readlane_b32 s67, v234, 17
	s_branch .LBB0_28

.LBB0_587:
	s_cmp_lg_u32 s2, 0
	s_cbranch_scc1 .Lwd_skip
	s_cmp_lt_u32 s50, 56
	s_cbranch_scc1 .Lwd_skip
	v_readlane_b32 s12, v234, 4
	v_readlane_b32 s13, v234, 5
	s_add_u32 s0, s80, 0x400000
	s_addc_u32 s1, s81, 0
	s_lshr_b32 s5, s52, 4
	s_lshl_b32 s5, s5, 3
	s_add_u32 s5, s5, s50
	s_sub_u32 s5, s5, 56
	s_lshl_b32 s6, s5, 8
	v_add_u32_e32 v18, s6, v156
	v_add_u32_e32 v18, 0x1f000, v18
	v_mov_b32_e32 v101, 0x8421100
	v_mov_b32_e32 v102, 0x300
	s_mov_b32 s4, 0
.Lwd_loop:
	v_lshrrev_b32_e32 v19, 6, v18
	v_lshrrev_b32_e32 v2, 2, v19
	v_mul_hi_u32 v12, v2, v101
	v_mul_u32_u24_e32 v3, 31, v12
	v_sub_u32_e32 v3, v2, v3
	v_and_b32_e32 v8, 3, v19
	v_lshl_or_b32 v3, v3, 2, v8
	v_bfe_u32 v8, v18, 3, 3
	v_lshl_or_b32 v3, v3, 3, v8
	v_and_b32_e32 v8, 7, v18
	v_lshl_or_b32 v2, v12, 3, v8
	v_lshlrev_b32_e32 v8, 2, v3
	v_lshrrev_b32_e32 v9, 4, v3
	v_and_b32_e32 v10, 60, v8
	v_cmp_lt_u32_e32 vcc, 11, v9
	s_nop 1
	v_cndmask_b32_e64 v19, 0, 4, vcc
	v_cmp_lt_u32_e32 vcc, 35, v9
	s_nop 1
	v_cndmask_b32_e64 v19, v19, 28, vcc
	v_bfe_u32 v12, v10, 4, 1
	v_lshrrev_b32_e32 v3, 5, v10
	v_sub_u32_e32 v12, v12, v3
	v_lshlrev_b32_e32 v12, 4, v12
	v_add_u32_e32 v3, 0xffffffd4, v9
	v_cmp_gt_u32_e32 vcc, 8, v3
	s_nop 1
	v_cndmask_b32_e64 v12, 0, v12, vcc
	v_add3_u32 v19, v8, v19, v12
	v_add_u32_e32 v3, 0x900, v10
	v_cmp_eq_u32_e32 vcc, 0, v10
	s_nop 1
	v_cndmask_b32_e32 v3, v3, v102, vcc
	v_cmp_eq_u32_e32 vcc, 60, v9
	s_nop 1
	v_cndmask_b32_e32 v19, v19, v3, vcc
	v_lshl_or_b32 v3, v9, 6, v10
	v_cmp_gt_u32_e32 vcc, 0xf1c, v3
	s_nop 1
	v_cndmask_b32_e64 v17, 0, 1, vcc
	s_nop 1
	v_cndmask_b32_e64 v19, 0, v19, vcc
	v_mul_u32_u24_e32 v14, 0x1e380, v2
	v_lshl_add_u32 v14, v19, 2, v14
	v_lshrrev_b32_e32 v12, 7, v2
	v_mul_u32_u24_e32 v15, 0x7c0000, v12
	v_lshl_add_u32 v15, v8, 11, v15
	v_and_b32_e32 v12, 0x7f, v2
	v_lshl_add_u32 v15, v12, 4, v15
	v_add_u32_e32 v16, 0x1000, v15
	global_load_dwordx4 v[20:23], v14, s[12:13]
	v_add_u32_e32 v14, 0x3c70, v14
	global_load_dwordx4 v[24:27], v14, s[12:13]
	v_add_u32_e32 v14, 0x3c70, v14
	global_load_dwordx4 v[28:31], v14, s[12:13]
	v_add_u32_e32 v14, 0x3c70, v14
	global_load_dwordx4 v[32:35], v14, s[12:13]
	v_add_u32_e32 v14, 0x3c70, v14
	global_load_dwordx4 v[36:39], v14, s[12:13]
	v_add_u32_e32 v14, 0x3c70, v14
	global_load_dwordx4 v[40:43], v14, s[12:13]
	v_add_u32_e32 v14, 0x3c70, v14
	global_load_dwordx4 v[44:47], v14, s[12:13]
	v_add_u32_e32 v14, 0x3c70, v14
	global_load_dwordx4 v[48:51], v14, s[12:13]
	v_add_u32_e32 v11, 0x4000, v18
	s_cmp_eq_u32 s4, 3
	s_cselect_b32 s7, 1, 0
	s_cmp_ge_u32 s5, 48
	s_cselect_b32 s8, 1, 0
	s_and_b32 s7, s7, s8
	s_cmp_eq_u32 s7, 1
	s_cbranch_scc0 .Lwd_two
	v_mov_b32_e32 v11, v18
.Lwd_two:
	v_lshrrev_b32_e32 v19, 6, v11
	v_lshrrev_b32_e32 v2, 2, v19
	v_mul_hi_u32 v12, v2, v101
	v_mul_u32_u24_e32 v3, 31, v12
	v_sub_u32_e32 v3, v2, v3
	v_and_b32_e32 v8, 3, v19
	v_lshl_or_b32 v3, v3, 2, v8
	v_bfe_u32 v8, v11, 3, 3
	v_lshl_or_b32 v3, v3, 3, v8
	v_and_b32_e32 v8, 7, v11
	v_lshl_or_b32 v2, v12, 3, v8
	v_lshlrev_b32_e32 v8, 2, v3
	v_lshrrev_b32_e32 v9, 4, v3
	v_and_b32_e32 v10, 60, v8
	v_cmp_lt_u32_e32 vcc, 11, v9
	s_nop 1
	v_cndmask_b32_e64 v19, 0, 4, vcc
	v_cmp_lt_u32_e32 vcc, 35, v9
	s_nop 1
	v_cndmask_b32_e64 v19, v19, 28, vcc
	v_bfe_u32 v12, v10, 4, 1
	v_lshrrev_b32_e32 v3, 5, v10
	v_sub_u32_e32 v12, v12, v3
	v_lshlrev_b32_e32 v12, 4, v12
	v_add_u32_e32 v3, 0xffffffd4, v9
	v_cmp_gt_u32_e32 vcc, 8, v3
	s_nop 1
	v_cndmask_b32_e64 v12, 0, v12, vcc
	v_add3_u32 v19, v8, v19, v12
	v_add_u32_e32 v3, 0x900, v10
	v_cmp_eq_u32_e32 vcc, 0, v10
	s_nop 1
	v_cndmask_b32_e32 v3, v3, v102, vcc
	v_cmp_eq_u32_e32 vcc, 60, v9
	s_nop 1
	v_cndmask_b32_e32 v19, v19, v3, vcc
	v_lshl_or_b32 v3, v9, 6, v10
	v_cmp_gt_u32_e32 vcc, 0xf1c, v3
	s_nop 1
	v_cndmask_b32_e64 v107, 0, 1, vcc
	s_nop 1
	v_cndmask_b32_e64 v19, 0, v19, vcc
	v_mul_u32_u24_e32 v104, 0x1e380, v2
	v_lshl_add_u32 v104, v19, 2, v104
	v_lshrrev_b32_e32 v12, 7, v2
	v_mul_u32_u24_e32 v105, 0x7c0000, v12
	v_lshl_add_u32 v105, v8, 11, v105
	v_and_b32_e32 v12, 0x7f, v2
	v_lshl_add_u32 v105, v12, 4, v105
	v_add_u32_e32 v106, 0x1000, v105
	global_load_dwordx4 v[52:55], v104, s[12:13]
	v_add_u32_e32 v104, 0x3c70, v104
	global_load_dwordx4 v[56:59], v104, s[12:13]
	v_add_u32_e32 v104, 0x3c70, v104
	global_load_dwordx4 v[60:63], v104, s[12:13]
	v_add_u32_e32 v104, 0x3c70, v104
	global_load_dwordx4 v[64:67], v104, s[12:13]
	v_add_u32_e32 v104, 0x3c70, v104
	global_load_dwordx4 v[68:71], v104, s[12:13]
	v_add_u32_e32 v104, 0x3c70, v104
	global_load_dwordx4 v[72:75], v104, s[12:13]
	v_add_u32_e32 v104, 0x3c70, v104
	global_load_dwordx4 v[76:79], v104, s[12:13]
	v_add_u32_e32 v104, 0x3c70, v104
	global_load_dwordx4 v[80:83], v104, s[12:13]
	s_waitcnt vmcnt(8)
	v_cvt_pk_bf16_f32 v84, v20, v24
	v_cvt_pk_bf16_f32 v85, v28, v32
	v_cvt_pk_bf16_f32 v86, v36, v40
	v_cvt_pk_bf16_f32 v87, v44, v48
	v_cvt_pk_bf16_f32 v88, v21, v25
	v_cvt_pk_bf16_f32 v89, v29, v33
	v_cvt_pk_bf16_f32 v90, v37, v41
	v_cvt_pk_bf16_f32 v91, v45, v49
	v_cvt_pk_bf16_f32 v92, v22, v26
	v_cvt_pk_bf16_f32 v93, v30, v34
	v_cvt_pk_bf16_f32 v94, v38, v42
	v_cvt_pk_bf16_f32 v95, v46, v50
	v_cvt_pk_bf16_f32 v96, v23, v27
	v_cvt_pk_bf16_f32 v97, v31, v35
	v_cvt_pk_bf16_f32 v98, v39, v43
	v_cvt_pk_bf16_f32 v99, v47, v51
	v_cmp_ne_u32_e32 vcc, 0, v17
	s_nop 1
	v_cndmask_b32_e64 v84, 0, v84, vcc
	v_cndmask_b32_e64 v85, 0, v85, vcc
	v_cndmask_b32_e64 v86, 0, v86, vcc
	v_cndmask_b32_e64 v87, 0, v87, vcc
	v_cndmask_b32_e64 v88, 0, v88, vcc
	v_cndmask_b32_e64 v89, 0, v89, vcc
	v_cndmask_b32_e64 v90, 0, v90, vcc
	v_cndmask_b32_e64 v91, 0, v91, vcc
	v_cndmask_b32_e64 v92, 0, v92, vcc
	v_cndmask_b32_e64 v93, 0, v93, vcc
	v_cndmask_b32_e64 v94, 0, v94, vcc
	v_cndmask_b32_e64 v95, 0, v95, vcc
	v_cndmask_b32_e64 v96, 0, v96, vcc
	v_cndmask_b32_e64 v97, 0, v97, vcc
	v_cndmask_b32_e64 v98, 0, v98, vcc
	v_cndmask_b32_e64 v99, 0, v99, vcc
	global_store_dwordx4 v15, v[84:87], s[0:1]
	global_store_dwordx4 v15, v[88:91], s[0:1] offset:2048
	global_store_dwordx4 v16, v[92:95], s[0:1]
	global_store_dwordx4 v16, v[96:99], s[0:1] offset:2048
	s_waitcnt vmcnt(4)
	s_cmp_eq_u32 s7, 1
	s_cbranch_scc1 .Lwd_done
	s_nop 0
	v_cvt_pk_bf16_f32 v84, v52, v56
	v_cvt_pk_bf16_f32 v85, v60, v64
	v_cvt_pk_bf16_f32 v86, v68, v72
	v_cvt_pk_bf16_f32 v87, v76, v80
	v_cvt_pk_bf16_f32 v88, v53, v57
	v_cvt_pk_bf16_f32 v89, v61, v65
	v_cvt_pk_bf16_f32 v90, v69, v73
	v_cvt_pk_bf16_f32 v91, v77, v81
	v_cvt_pk_bf16_f32 v92, v54, v58
	v_cvt_pk_bf16_f32 v93, v62, v66
	v_cvt_pk_bf16_f32 v94, v70, v74
	v_cvt_pk_bf16_f32 v95, v78, v82
	v_cvt_pk_bf16_f32 v96, v55, v59
	v_cvt_pk_bf16_f32 v97, v63, v67
	v_cvt_pk_bf16_f32 v98, v71, v75
	v_cvt_pk_bf16_f32 v99, v79, v83
	v_cmp_ne_u32_e32 vcc, 0, v107
	s_nop 1
	v_cndmask_b32_e64 v84, 0, v84, vcc
	v_cndmask_b32_e64 v85, 0, v85, vcc
	v_cndmask_b32_e64 v86, 0, v86, vcc
	v_cndmask_b32_e64 v87, 0, v87, vcc
	v_cndmask_b32_e64 v88, 0, v88, vcc
	v_cndmask_b32_e64 v89, 0, v89, vcc
	v_cndmask_b32_e64 v90, 0, v90, vcc
	v_cndmask_b32_e64 v91, 0, v91, vcc
	v_cndmask_b32_e64 v92, 0, v92, vcc
	v_cndmask_b32_e64 v93, 0, v93, vcc
	v_cndmask_b32_e64 v94, 0, v94, vcc
	v_cndmask_b32_e64 v95, 0, v95, vcc
	v_cndmask_b32_e64 v96, 0, v96, vcc
	v_cndmask_b32_e64 v97, 0, v97, vcc
	v_cndmask_b32_e64 v98, 0, v98, vcc
	v_cndmask_b32_e64 v99, 0, v99, vcc
	global_store_dwordx4 v105, v[84:87], s[0:1]
	global_store_dwordx4 v105, v[88:91], s[0:1] offset:2048
	global_store_dwordx4 v106, v[92:95], s[0:1]
	global_store_dwordx4 v106, v[96:99], s[0:1] offset:2048
	v_add_u32_e32 v18, 0x8000, v18
	s_add_u32 s4, s4, 1
	s_cmp_lt_u32 s4, 4
	s_cbranch_scc1 .Lwd_loop
.Lwd_done:
.Lwd_skip:
	s_waitcnt vmcnt(0)
	s_barrier
	s_mov_b64 s[0:1], exec
	v_readlane_b32 s4, v234, 0
	v_readlane_b32 s5, v234, 1
	v_readlane_b32 s18, v232, 33
	s_and_b64 s[4:5], s[0:1], s[4:5]
	v_readlane_b32 s19, v232, 34
	s_mov_b64 exec, s[4:5]
	s_cbranch_execz .LBB0_635
	s_waitcnt vmcnt(0) expcnt(0) lgkmcnt(0)
	ds_read_b32 v3, v158
	ds_read_b32 v2, v159
	global_atomic_add v4, v[120:121], v160, off sc0
	s_lshl_b32 s9, s2, 1
	s_add_u32 s9, s9, 1
	s_waitcnt vmcnt(0) lgkmcnt(0)
	v_readfirstlane_b32 s6, v4
	v_readfirstlane_b32 s7, v3
	v_readfirstlane_b32 s8, v2
	s_nop 3
	s_add_u32 s10, s9, 1
	s_mul_i32 s11, s10, s7
	s_add_u32 s6, s6, 1
	s_cmp_eq_u32 s6, s11
	s_cbranch_scc1 .Lfbp_leader
	s_mov_b32 s4, 0
